# v46 + Up epilogue: stale s_nops removed and rstd values loaded from the LDS table straight into their consumer registers (7 v_mov removed)
# baseline (speedup 1.0000x reference)
; __device__ __forceinline__ unsigned cvt_pk_bf16(float lo, float hi) { unsigned r; asm volatile("v_cvt_pk_bf16_f32 %0, %1, %2" : "=v"(r) : "v"(lo), "v"(hi)); return r; }
; __device__ __forceinline__ int lane_id_v() { int l; asm volatile("v_mbcnt_lo_u32_b32 %0, -1, 0\n\tv_mbcnt_hi_u32_b32 %0, -1, %0" : "=v"(l)); return l; }
; #define LAS __attribute__((address_space(3)))
;     __device__ __forceinline__ void operator()(const f32x4 (&acc)[2][2][4][2], const pg8::Unit& u, int wr, int wc, int fr_, int fq_) const {
;         const int lane_ = pg8::lane_id_v(); const int fr = lane_ & 15, fq = lane_ >> 4;
;         const int lrow0 = u.pm * 256 + wr * 64 + fr;
;         const int b = batch_of(rowbase + u.pm * 256);
;         f32x4 sv[2][2];
; #pragma unroll
;         for (int bj = 0; bj < 2; ++bj)
; #pragma unroll
;             for (int n = 0; n < 2; ++n) sv[bj][n] = *(const LAS f32x4*)(xl + 16384 + (bj * 128 + wc * 32 + 8 * fq + 4 * n) * 4);
;         float rs8[8]; rows_rstd8_lds(xl, wr * 64 + fr, fq, rs8);
;         const int hcol = u.pn * 128 + wc * 32 + 8 * fq;
; #pragma unroll
;         for (int ai = 0; ai < 2; ++ai)
; #pragma unroll
;             for (int m = 0; m < 4; ++m) {
;                 const int lr = lrow0 + ai * 128 + m * 16;
;                 const float rs = rs8[ai * 4 + m];
;                 const f32x4 g0 = acc[ai][0][m][0] * rs + sv[0][0], g1 = acc[ai][0][m][1] * rs + sv[0][1];
;                 const f32x4 u0 = acc[ai][1][m][0] * rs + sv[1][0], u1 = acc[ai][1][m][1] * rs + sv[1][1];
;                 const f32x2 ha = pg8::silu_mul_pk((f32x2){g0[0], g0[1]}, (f32x2){u0[0], u0[1]}), hb = pg8::silu_mul_pk((f32x2){g0[2], g0[3]}, (f32x2){u0[2], u0[3]});
;                 const f32x2 hc = pg8::silu_mul_pk((f32x2){g1[0], g1[1]}, (f32x2){u1[0], u1[1]}), hd = pg8::silu_mul_pk((f32x2){g1[2], g1[3]}, (f32x2){u1[2], u1[3]});
;                 u32x4 w; w.x = cvt_pk_bf16(ha.x, ha.y); w.y = cvt_pk_bf16(hb.x, hb.y); w.z = cvt_pk_bf16(hc.x, hc.y); w.w = cvt_pk_bf16(hd.x, hd.y);
.LBB0_379:
	v_mbcnt_lo_u32_b32 v228, -1, 0
	v_mbcnt_hi_u32_b32 v228, -1, v228
	v_and_b32_e32 v224, 15, v228
	v_add_u32_e32 v224, s91, v224
	v_lshlrev_b32_e32 v224, 2, v224
	v_add_u32_e32 v224, 0x26800, v224
	ds_read_b32 v172, v224
	ds_read_b32 v170, v224 offset:64
	ds_read_b32 v168, v224 offset:128
	ds_read_b32 v166, v224 offset:192
	ds_read_b32 v164, v224 offset:512
	ds_read_b32 v162, v224 offset:576
	ds_read_b32 v160, v224 offset:640
	ds_read_b32 v215, v224 offset:704
	v_mbcnt_lo_u32_b32 v158, -1, 0
	v_mbcnt_hi_u32_b32 v158, -1, v158
	s_add_i32 s23, s23, s91
	v_and_b32_e32 v159, 15, v158
	v_or_b32_e32 v165, s23, v159
	v_ashrrev_i32_e32 v167, 4, v158
	v_readlane_b32 s26, v252, 22
	s_add_i32 s23, 0, 0x22400
	v_lshl_add_u32 v80, v167, 5, s26
	ds_read_b128 v[92:95], v80
	ds_read_b128 v[88:91], v80 offset:16
	ds_read_b128 v[84:87], v80 offset:512
	ds_read_b128 v[80:83], v80 offset:528
	s_mov_b32 s26, 0x358637bd
	s_lshl_b32 s2, s2, 7
	s_waitcnt lgkmcnt(0)
	s_or_b32 s2, s2, s15
	s_mov_b64 s[76:77], s[62:63]
	v_pk_fma_f32 v[126:127], v[126:127], v[170:171], v[94:95] op_sel_hi:[1,0,1]
	v_pk_fma_f32 v[124:125], v[124:125], v[170:171], v[92:93] op_sel_hi:[1,0,1]
	v_pk_fma_f32 v[116:117], v[116:117], v[170:171], v[84:85] op_sel_hi:[1,0,1]
	v_pk_fma_f32 v[118:119], v[118:119], v[170:171], v[86:87] op_sel_hi:[1,0,1]
	v_pk_mul_f32 v[116:117], v[124:125], v[116:117]
	v_pk_fma_f32 v[120:121], v[120:121], v[170:171], v[88:89] op_sel_hi:[1,0,1]
	v_pk_mul_f32 v[118:119], v[126:127], v[118:119]
	v_pk_fma_f32 v[112:113], v[112:113], v[170:171], v[80:81] op_sel_hi:[1,0,1]
	v_pk_fma_f32 v[122:123], v[122:123], v[170:171], v[90:91] op_sel_hi:[1,0,1]
	v_pk_mul_f32 v[112:113], v[120:121], v[112:113]
	v_pk_fma_f32 v[114:115], v[114:115], v[170:171], v[82:83] op_sel_hi:[1,0,1]
	v_pk_mul_f32 v[114:115], v[122:123], v[114:115]
	v_pk_fma_f32 v[110:111], v[110:111], v[168:169], v[94:95] op_sel_hi:[1,0,1]
	v_pk_fma_f32 v[108:109], v[108:109], v[168:169], v[92:93] op_sel_hi:[1,0,1]
	v_pk_fma_f32 v[100:101], v[100:101], v[168:169], v[84:85] op_sel_hi:[1,0,1]
	v_pk_mul_f32 v[100:101], v[108:109], v[100:101]
	v_pk_fma_f32 v[102:103], v[102:103], v[168:169], v[86:87] op_sel_hi:[1,0,1]
	v_pk_fma_f32 v[104:105], v[104:105], v[168:169], v[88:89] op_sel_hi:[1,0,1]
	v_pk_mul_f32 v[102:103], v[110:111], v[102:103]
	v_pk_fma_f32 v[96:97], v[96:97], v[168:169], v[80:81] op_sel_hi:[1,0,1]
	v_pk_fma_f32 v[106:107], v[106:107], v[168:169], v[90:91] op_sel_hi:[1,0,1]
	v_pk_mul_f32 v[96:97], v[104:105], v[96:97]
	v_pk_fma_f32 v[98:99], v[98:99], v[168:169], v[82:83] op_sel_hi:[1,0,1]
	v_pk_fma_f32 v[78:79], v[78:79], v[166:167], v[94:95] op_sel_hi:[1,0,1]
	v_pk_mul_f32 v[98:99], v[106:107], v[98:99]
	v_pk_fma_f32 v[76:77], v[76:77], v[166:167], v[92:93] op_sel_hi:[1,0,1]
	v_pk_fma_f32 v[68:69], v[68:69], v[166:167], v[84:85] op_sel_hi:[1,0,1]
	v_pk_mul_f32 v[68:69], v[76:77], v[68:69]
	v_pk_fma_f32 v[70:71], v[70:71], v[166:167], v[86:87] op_sel_hi:[1,0,1]
	v_pk_fma_f32 v[72:73], v[72:73], v[166:167], v[88:89] op_sel_hi:[1,0,1]
	v_pk_mul_f32 v[70:71], v[78:79], v[70:71]
	v_pk_fma_f32 v[64:65], v[64:65], v[166:167], v[80:81] op_sel_hi:[1,0,1]
	v_pk_fma_f32 v[74:75], v[74:75], v[166:167], v[90:91] op_sel_hi:[1,0,1]
	v_pk_mul_f32 v[64:65], v[72:73], v[64:65]
	v_pk_fma_f32 v[142:143], v[142:143], v[172:173], v[94:95] op_sel_hi:[1,0,1]
	v_pk_fma_f32 v[140:141], v[140:141], v[172:173], v[92:93] op_sel_hi:[1,0,1]
	v_pk_fma_f32 v[132:133], v[132:133], v[172:173], v[84:85] op_sel_hi:[1,0,1]
	v_pk_fma_f32 v[138:139], v[138:139], v[172:173], v[90:91] op_sel_hi:[1,0,1]
	v_pk_fma_f32 v[136:137], v[136:137], v[172:173], v[88:89] op_sel_hi:[1,0,1]
	v_pk_fma_f32 v[134:135], v[134:135], v[172:173], v[86:87] op_sel_hi:[1,0,1]
	v_pk_fma_f32 v[128:129], v[128:129], v[172:173], v[80:81] op_sel_hi:[1,0,1]
	v_pk_fma_f32 v[130:131], v[130:131], v[172:173], v[82:83] op_sel_hi:[1,0,1]
	v_pk_mul_f32 v[172:173], v[140:141], s[88:89] op_sel_hi:[1,0]
	v_pk_mul_f32 v[132:133], v[140:141], v[132:133]
	v_pk_mul_f32 v[140:141], v[142:143], s[88:89] op_sel_hi:[1,0]
	v_exp_f32_e32 v140, v140
	v_exp_f32_e32 v141, v141
	s_nop 0
	v_pk_add_f32 v[140:141], v[140:141], 1.0 op_sel_hi:[1,0]
	v_rcp_f32_e32 v140, v140
	v_rcp_f32_e32 v141, v141
	v_pk_mul_f32 v[134:135], v[142:143], v[134:135]
	v_exp_f32_e32 v172, v172
	v_pk_mul_f32 v[134:135], v[134:135], v[140:141]
	v_pk_mul_f32 v[140:141], v[136:137], s[88:89] op_sel_hi:[1,0]
	v_exp_f32_e32 v173, v173
	v_exp_f32_e32 v140, v140
	v_exp_f32_e32 v141, v141
	v_pk_mul_f32 v[128:129], v[136:137], v[128:129]
	v_pk_mul_f32 v[136:137], v[138:139], s[88:89] op_sel_hi:[1,0]
	v_exp_f32_e32 v136, v136
	v_exp_f32_e32 v137, v137
	v_pk_add_f32 v[172:173], v[172:173], 1.0 op_sel_hi:[1,0]
	v_pk_add_f32 v[140:141], v[140:141], 1.0 op_sel_hi:[1,0]
	v_rcp_f32_e32 v172, v172
	v_rcp_f32_e32 v173, v173
	v_rcp_f32_e32 v140, v140
	v_rcp_f32_e32 v141, v141
	v_pk_add_f32 v[136:137], v[136:137], 1.0 op_sel_hi:[1,0]
	v_rcp_f32_e32 v136, v136
	v_rcp_f32_e32 v137, v137
	v_lshl_add_u32 v174, v167, 3, s2
	v_pk_mul_f32 v[132:133], v[132:133], v[172:173]
	v_pk_mul_f32 v[130:131], v[138:139], v[130:131]
	v_pk_mul_f32 v[128:129], v[128:129], v[140:141]
	v_ashrrev_i32_e32 v175, 31, v174
	v_pk_mul_f32 v[130:131], v[130:131], v[136:137]
	v_cvt_pk_bf16_f32 v132, v132, v133
	v_cvt_pk_bf16_f32 v133, v134, v135
	v_cvt_pk_bf16_f32 v134, v128, v129
	v_mov_b64_e32 v[128:129], s[30:31]
	s_movk_i32 s2, 0x1600
	v_cvt_pk_bf16_f32 v135, v130, v131
	v_mad_i64_i32 v[136:137], s[26:27], v165, s2, v[128:129]
	v_lshlrev_b64 v[130:131], 1, v[174:175]
	v_lshl_add_u64 v[136:137], v[136:137], 0, v[130:131]
	global_store_dwordx4 v[136:137], v[132:135], off
; __device__ __forceinline__ unsigned cvt_pk_bf16(float lo, float hi) { unsigned r; asm volatile("v_cvt_pk_bf16_f32 %0, %1, %2" : "=v"(r) : "v"(lo), "v"(hi)); return r; }
;     __device__ __forceinline__ void operator()(const f32x4 (&acc)[2][2][4][2], const pg8::Unit& u, int wr, int wc, int fr_, int fq_) const {
;     ...
;                 const int lr = lrow0 + ai * 128 + m * 16;
;                 const float rs = rs8[ai * 4 + m];
;                 const f32x4 g0 = acc[ai][0][m][0] * rs + sv[0][0], g1 = acc[ai][0][m][1] * rs + sv[0][1];
;                 const f32x4 u0 = acc[ai][1][m][0] * rs + sv[1][0], u1 = acc[ai][1][m][1] * rs + sv[1][1];
;                 const f32x2 ha = pg8::silu_mul_pk((f32x2){g0[0], g0[1]}, (f32x2){u0[0], u0[1]}), hb = pg8::silu_mul_pk((f32x2){g0[2], g0[3]}, (f32x2){u0[2], u0[3]});
;                 const f32x2 hc = pg8::silu_mul_pk((f32x2){g1[0], g1[1]}, (f32x2){u1[0], u1[1]}), hd = pg8::silu_mul_pk((f32x2){g1[2], g1[3]}, (f32x2){u1[2], u1[3]});
;                 u32x4 w; w.x = cvt_pk_bf16(ha.x, ha.y); w.y = cvt_pk_bf16(hb.x, hb.y); w.z = cvt_pk_bf16(hc.x, hc.y); w.w = cvt_pk_bf16(hd.x, hd.y);
;                 *(u32x4*)(H + (size_t)lr * FF + hcol) = w;
	v_pk_fma_f32 v[66:67], v[66:67], v[166:167], v[82:83] op_sel_hi:[1,0,1]
	v_pk_fma_f32 v[62:63], v[62:63], v[164:165], v[94:95] op_sel_hi:[1,0,1]
	v_pk_mul_f32 v[132:133], v[124:125], s[88:89] op_sel_hi:[1,0]
	v_pk_mul_f32 v[124:125], v[126:127], s[88:89] op_sel_hi:[1,0]
	v_exp_f32_e32 v132, v132
	v_exp_f32_e32 v124, v124
	v_exp_f32_e32 v125, v125
	v_exp_f32_e32 v133, v133
	v_or_b32_e32 v134, 16, v165
	v_pk_mul_f32 v[66:67], v[74:75], v[66:67]
	v_pk_add_f32 v[124:125], v[124:125], 1.0 op_sel_hi:[1,0]
	v_pk_add_f32 v[132:133], v[132:133], 1.0 op_sel_hi:[1,0]
	v_rcp_f32_e32 v124, v124
	v_rcp_f32_e32 v125, v125
	v_rcp_f32_e32 v132, v132
	v_rcp_f32_e32 v133, v133
	v_pk_fma_f32 v[60:61], v[60:61], v[164:165], v[92:93] op_sel_hi:[1,0,1]
	v_pk_mul_f32 v[118:119], v[118:119], v[124:125]
	v_pk_mul_f32 v[124:125], v[120:121], s[88:89] op_sel_hi:[1,0]
	v_pk_mul_f32 v[116:117], v[116:117], v[132:133]
	v_exp_f32_e32 v124, v124
	v_exp_f32_e32 v125, v125
	v_pk_fma_f32 v[52:53], v[52:53], v[164:165], v[84:85] op_sel_hi:[1,0,1]
	v_pk_fma_f32 v[54:55], v[54:55], v[164:165], v[86:87] op_sel_hi:[1,0,1]
	v_pk_mul_f32 v[52:53], v[60:61], v[52:53]
	v_pk_add_f32 v[124:125], v[124:125], 1.0 op_sel_hi:[1,0]
	v_pk_fma_f32 v[56:57], v[56:57], v[164:165], v[88:89] op_sel_hi:[1,0,1]
	v_rcp_f32_e32 v124, v124
	v_rcp_f32_e32 v125, v125
	v_pk_mul_f32 v[54:55], v[62:63], v[54:55]
	v_pk_fma_f32 v[48:49], v[48:49], v[164:165], v[80:81] op_sel_hi:[1,0,1]
	v_pk_fma_f32 v[58:59], v[58:59], v[164:165], v[90:91] op_sel_hi:[1,0,1]
	v_pk_mul_f32 v[120:121], v[112:113], v[124:125]
	v_pk_mul_f32 v[112:113], v[122:123], s[88:89] op_sel_hi:[1,0]
	v_pk_mul_f32 v[48:49], v[56:57], v[48:49]
	v_exp_f32_e32 v112, v112
	v_exp_f32_e32 v113, v113
	v_pk_fma_f32 v[50:51], v[50:51], v[164:165], v[82:83] op_sel_hi:[1,0,1]
	v_pk_fma_f32 v[46:47], v[46:47], v[162:163], v[94:95] op_sel_hi:[1,0,1]
	v_pk_mul_f32 v[50:51], v[58:59], v[50:51]
	v_pk_add_f32 v[112:113], v[112:113], 1.0 op_sel_hi:[1,0]
	v_pk_fma_f32 v[44:45], v[44:45], v[162:163], v[92:93] op_sel_hi:[1,0,1]
	v_rcp_f32_e32 v112, v112
	v_rcp_f32_e32 v113, v113
	v_pk_fma_f32 v[36:37], v[36:37], v[162:163], v[84:85] op_sel_hi:[1,0,1]
	v_pk_fma_f32 v[38:39], v[38:39], v[162:163], v[86:87] op_sel_hi:[1,0,1]
	v_pk_mul_f32 v[36:37], v[44:45], v[36:37]
	v_pk_mul_f32 v[122:123], v[114:115], v[112:113]
	v_cvt_pk_bf16_f32 v112, v116, v117
	v_mad_i64_i32 v[116:117], s[26:27], v134, s2, v[128:129]
	v_cvt_pk_bf16_f32 v113, v118, v119
	v_lshl_add_u64 v[116:117], v[116:117], 0, v[130:131]
	v_cvt_pk_bf16_f32 v114, v120, v121
	v_cvt_pk_bf16_f32 v115, v122, v123
	global_store_dwordx4 v[116:117], v[112:115], off
	v_pk_fma_f32 v[40:41], v[40:41], v[162:163], v[88:89] op_sel_hi:[1,0,1]
	v_pk_mul_f32 v[38:39], v[46:47], v[38:39]
	v_pk_mul_f32 v[112:113], v[108:109], s[88:89] op_sel_hi:[1,0]
	v_pk_mul_f32 v[108:109], v[110:111], s[88:89] op_sel_hi:[1,0]
	v_exp_f32_e32 v112, v112
	v_exp_f32_e32 v108, v108
	v_exp_f32_e32 v109, v109
	v_exp_f32_e32 v113, v113
	v_or_b32_e32 v114, 32, v165
	v_pk_fma_f32 v[32:33], v[32:33], v[162:163], v[80:81] op_sel_hi:[1,0,1]
	v_pk_add_f32 v[108:109], v[108:109], 1.0 op_sel_hi:[1,0]
	v_pk_add_f32 v[112:113], v[112:113], 1.0 op_sel_hi:[1,0]
	v_rcp_f32_e32 v108, v108
	v_rcp_f32_e32 v109, v109
	v_rcp_f32_e32 v112, v112
	v_rcp_f32_e32 v113, v113
	v_pk_fma_f32 v[42:43], v[42:43], v[162:163], v[90:91] op_sel_hi:[1,0,1]
	v_pk_mul_f32 v[102:103], v[102:103], v[108:109]
	v_pk_mul_f32 v[108:109], v[104:105], s[88:89] op_sel_hi:[1,0]
	v_pk_mul_f32 v[100:101], v[100:101], v[112:113]
	v_exp_f32_e32 v108, v108
	v_exp_f32_e32 v109, v109
	v_pk_mul_f32 v[32:33], v[40:41], v[32:33]
	v_pk_add_f32 v[108:109], v[108:109], 1.0 op_sel_hi:[1,0]
	v_pk_fma_f32 v[34:35], v[34:35], v[162:163], v[82:83] op_sel_hi:[1,0,1]
	v_rcp_f32_e32 v108, v108
	v_rcp_f32_e32 v109, v109
	v_pk_mul_f32 v[34:35], v[42:43], v[34:35]
	v_pk_mul_f32 v[104:105], v[96:97], v[108:109]
	v_pk_mul_f32 v[96:97], v[106:107], s[88:89] op_sel_hi:[1,0]
	v_exp_f32_e32 v96, v96
	v_exp_f32_e32 v97, v97
	v_pk_fma_f32 v[30:31], v[30:31], v[160:161], v[94:95] op_sel_hi:[1,0,1]
	v_pk_fma_f32 v[28:29], v[28:29], v[160:161], v[92:93] op_sel_hi:[1,0,1]
	v_pk_add_f32 v[96:97], v[96:97], 1.0 op_sel_hi:[1,0]
	v_pk_fma_f32 v[20:21], v[20:21], v[160:161], v[84:85] op_sel_hi:[1,0,1]
	v_rcp_f32_e32 v96, v96
	v_rcp_f32_e32 v97, v97
	v_pk_mul_f32 v[20:21], v[28:29], v[20:21]
	v_pk_fma_f32 v[22:23], v[22:23], v[160:161], v[86:87] op_sel_hi:[1,0,1]
	v_pk_fma_f32 v[24:25], v[24:25], v[160:161], v[88:89] op_sel_hi:[1,0,1]
	v_pk_mul_f32 v[106:107], v[98:99], v[96:97]
	v_cvt_pk_bf16_f32 v96, v100, v101
	v_mad_i64_i32 v[100:101], s[26:27], v114, s2, v[128:129]
	v_cvt_pk_bf16_f32 v97, v102, v103
	v_lshl_add_u64 v[100:101], v[100:101], 0, v[130:131]
	v_cvt_pk_bf16_f32 v98, v104, v105
	v_cvt_pk_bf16_f32 v99, v106, v107
	global_store_dwordx4 v[100:101], v[96:99], off
	v_pk_mul_f32 v[22:23], v[30:31], v[22:23]
	v_pk_fma_f32 v[16:17], v[16:17], v[160:161], v[80:81] op_sel_hi:[1,0,1]
	v_pk_mul_f32 v[96:97], v[76:77], s[88:89] op_sel_hi:[1,0]
	v_pk_mul_f32 v[76:77], v[78:79], s[88:89] op_sel_hi:[1,0]
	v_exp_f32_e32 v96, v96
	v_exp_f32_e32 v76, v76
	v_exp_f32_e32 v77, v77
	v_exp_f32_e32 v97, v97
	v_or_b32_e32 v98, 48, v165
	v_pk_fma_f32 v[26:27], v[26:27], v[160:161], v[90:91] op_sel_hi:[1,0,1]
	v_pk_add_f32 v[76:77], v[76:77], 1.0 op_sel_hi:[1,0]
	v_pk_add_f32 v[96:97], v[96:97], 1.0 op_sel_hi:[1,0]
	v_rcp_f32_e32 v76, v76
	v_rcp_f32_e32 v77, v77
	v_rcp_f32_e32 v96, v96
	v_rcp_f32_e32 v97, v97
	v_pk_mul_f32 v[16:17], v[24:25], v[16:17]
	v_pk_mul_f32 v[70:71], v[70:71], v[76:77]
	v_pk_mul_f32 v[76:77], v[72:73], s[88:89] op_sel_hi:[1,0]
; __device__ __forceinline__ unsigned cvt_pk_bf16(float lo, float hi) { unsigned r; asm volatile("v_cvt_pk_bf16_f32 %0, %1, %2" : "=v"(r) : "v"(lo), "v"(hi)); return r; }
;     __device__ __forceinline__ void operator()(const f32x4 (&acc)[2][2][4][2], const pg8::Unit& u, int wr, int wc, int fr_, int fq_) const {
;     ...
;                 const int lr = lrow0 + ai * 128 + m * 16;
;                 const float rs = rs8[ai * 4 + m];
;                 const f32x4 g0 = acc[ai][0][m][0] * rs + sv[0][0], g1 = acc[ai][0][m][1] * rs + sv[0][1];
;                 const f32x4 u0 = acc[ai][1][m][0] * rs + sv[1][0], u1 = acc[ai][1][m][1] * rs + sv[1][1];
;                 const f32x2 ha = pg8::silu_mul_pk((f32x2){g0[0], g0[1]}, (f32x2){u0[0], u0[1]}), hb = pg8::silu_mul_pk((f32x2){g0[2], g0[3]}, (f32x2){u0[2], u0[3]});
;                 const f32x2 hc = pg8::silu_mul_pk((f32x2){g1[0], g1[1]}, (f32x2){u1[0], u1[1]}), hd = pg8::silu_mul_pk((f32x2){g1[2], g1[3]}, (f32x2){u1[2], u1[3]});
;                 u32x4 w; w.x = cvt_pk_bf16(ha.x, ha.y); w.y = cvt_pk_bf16(hb.x, hb.y); w.z = cvt_pk_bf16(hc.x, hc.y); w.w = cvt_pk_bf16(hd.x, hd.y);
;                 *(u32x4*)(H + (size_t)lr * FF + hcol) = w;
	v_pk_mul_f32 v[68:69], v[68:69], v[96:97]
	v_exp_f32_e32 v76, v76
	v_exp_f32_e32 v77, v77
	v_pk_fma_f32 v[18:19], v[18:19], v[160:161], v[82:83] op_sel_hi:[1,0,1]
	v_pk_add_f32 v[76:77], v[76:77], 1.0 op_sel_hi:[1,0]
	v_rcp_f32_e32 v76, v76
	v_rcp_f32_e32 v77, v77
	v_pk_mul_f32 v[18:19], v[26:27], v[18:19]
	v_pk_mul_f32 v[72:73], v[64:65], v[76:77]
	v_pk_mul_f32 v[64:65], v[74:75], s[88:89] op_sel_hi:[1,0]
	v_exp_f32_e32 v64, v64
	v_exp_f32_e32 v65, v65
	v_mov_b32_e32 v158, v215
	v_pk_fma_f32 v[14:15], v[14:15], v[158:159], v[94:95] op_sel_hi:[1,0,1]
	v_pk_fma_f32 v[12:13], v[12:13], v[158:159], v[92:93] op_sel_hi:[1,0,1]
	v_pk_add_f32 v[64:65], v[64:65], 1.0 op_sel_hi:[1,0]
	v_pk_fma_f32 v[4:5], v[4:5], v[158:159], v[84:85] op_sel_hi:[1,0,1]
	v_rcp_f32_e32 v64, v64
	v_rcp_f32_e32 v65, v65
	v_pk_mul_f32 v[4:5], v[12:13], v[4:5]
	v_pk_fma_f32 v[6:7], v[6:7], v[158:159], v[86:87] op_sel_hi:[1,0,1]
	v_pk_fma_f32 v[8:9], v[8:9], v[158:159], v[88:89] op_sel_hi:[1,0,1]
	v_pk_mul_f32 v[74:75], v[66:67], v[64:65]
	v_cvt_pk_bf16_f32 v64, v68, v69
	v_mad_i64_i32 v[68:69], s[26:27], v98, s2, v[128:129]
	v_cvt_pk_bf16_f32 v65, v70, v71
	v_lshl_add_u64 v[68:69], v[68:69], 0, v[130:131]
	v_cvt_pk_bf16_f32 v66, v72, v73
	v_cvt_pk_bf16_f32 v67, v74, v75
	global_store_dwordx4 v[68:69], v[64:67], off
	v_pk_mul_f32 v[6:7], v[14:15], v[6:7]
	v_pk_fma_f32 v[0:1], v[0:1], v[158:159], v[80:81] op_sel_hi:[1,0,1]
	v_pk_mul_f32 v[64:65], v[60:61], s[88:89] op_sel_hi:[1,0]
	v_pk_mul_f32 v[60:61], v[62:63], s[88:89] op_sel_hi:[1,0]
	v_exp_f32_e32 v64, v64
	v_exp_f32_e32 v60, v60
	v_exp_f32_e32 v61, v61
	v_exp_f32_e32 v65, v65
	v_add_u32_e32 v66, 0x80, v165
	v_pk_fma_f32 v[10:11], v[10:11], v[158:159], v[90:91] op_sel_hi:[1,0,1]
	v_pk_add_f32 v[60:61], v[60:61], 1.0 op_sel_hi:[1,0]
	v_pk_add_f32 v[64:65], v[64:65], 1.0 op_sel_hi:[1,0]
	v_rcp_f32_e32 v60, v60
	v_rcp_f32_e32 v61, v61
	v_rcp_f32_e32 v64, v64
	v_rcp_f32_e32 v65, v65
	v_pk_mul_f32 v[0:1], v[8:9], v[0:1]
	v_pk_mul_f32 v[54:55], v[54:55], v[60:61]
	v_pk_mul_f32 v[60:61], v[56:57], s[88:89] op_sel_hi:[1,0]
	v_pk_mul_f32 v[52:53], v[52:53], v[64:65]
	v_exp_f32_e32 v60, v60
	v_exp_f32_e32 v61, v61
	v_pk_fma_f32 v[2:3], v[2:3], v[158:159], v[82:83] op_sel_hi:[1,0,1]
	s_andn2_b64 vcc, exec, s[36:37]
	v_pk_mul_f32 v[2:3], v[10:11], v[2:3]
	v_pk_add_f32 v[60:61], v[60:61], 1.0 op_sel_hi:[1,0]
	s_nop 0
	v_rcp_f32_e32 v60, v60
	v_rcp_f32_e32 v61, v61
	s_nop 0
	v_pk_mul_f32 v[56:57], v[48:49], v[60:61]
	v_pk_mul_f32 v[48:49], v[58:59], s[88:89] op_sel_hi:[1,0]
	s_nop 0
	v_exp_f32_e32 v48, v48
	v_exp_f32_e32 v49, v49
	s_nop 0
	v_pk_add_f32 v[48:49], v[48:49], 1.0 op_sel_hi:[1,0]
	s_nop 0
	v_rcp_f32_e32 v48, v48
	v_rcp_f32_e32 v49, v49
	s_nop 0
	v_pk_mul_f32 v[58:59], v[50:51], v[48:49]
	v_cvt_pk_bf16_f32 v48, v52, v53
	v_mad_i64_i32 v[52:53], s[26:27], v66, s2, v[128:129]
	v_cvt_pk_bf16_f32 v49, v54, v55
	v_lshl_add_u64 v[52:53], v[52:53], 0, v[130:131]
	v_cvt_pk_bf16_f32 v50, v56, v57
	v_cvt_pk_bf16_f32 v51, v58, v59
	global_store_dwordx4 v[52:53], v[48:51], off
	s_nop 1
	v_pk_mul_f32 v[48:49], v[44:45], s[88:89] op_sel_hi:[1,0]
	v_pk_mul_f32 v[44:45], v[46:47], s[88:89] op_sel_hi:[1,0]
	v_exp_f32_e32 v48, v48
	v_exp_f32_e32 v44, v44
	v_exp_f32_e32 v45, v45
	v_exp_f32_e32 v49, v49
	v_add_u32_e32 v50, 0x90, v165
	v_pk_add_f32 v[44:45], v[44:45], 1.0 op_sel_hi:[1,0]
	s_nop 0
	v_rcp_f32_e32 v44, v44
	v_rcp_f32_e32 v45, v45
	v_pk_add_f32 v[48:49], v[48:49], 1.0 op_sel_hi:[1,0]
	v_pk_mul_f32 v[38:39], v[38:39], v[44:45]
	v_pk_mul_f32 v[44:45], v[40:41], s[88:89] op_sel_hi:[1,0]
	v_rcp_f32_e32 v48, v48
	v_exp_f32_e32 v44, v44
	v_exp_f32_e32 v45, v45
; __device__ __forceinline__ unsigned cvt_pk_bf16(float lo, float hi) { unsigned r; asm volatile("v_cvt_pk_bf16_f32 %0, %1, %2" : "=v"(r) : "v"(lo), "v"(hi)); return r; }
; template <class Epi, class Sched, bool ALIGN_EPI, bool SP2>
; __device__ __forceinline__ void gemm_phase(PG8_LAS unsigned char* lds, const Gemm g, const Sched& S, const Epi& E, int wid) {
;     ...
;         if (!has_next) break;
;     __device__ __forceinline__ void operator()(const f32x4 (&acc)[2][2][4][2], const pg8::Unit& u, int wr, int wc, int fr_, int fq_) const {
;     ...
;                 const int lr = lrow0 + ai * 128 + m * 16;
;                 const float rs = rs8[ai * 4 + m];
;                 const f32x4 g0 = acc[ai][0][m][0] * rs + sv[0][0], g1 = acc[ai][0][m][1] * rs + sv[0][1];
;                 const f32x4 u0 = acc[ai][1][m][0] * rs + sv[1][0], u1 = acc[ai][1][m][1] * rs + sv[1][1];
;                 const f32x2 ha = pg8::silu_mul_pk((f32x2){g0[0], g0[1]}, (f32x2){u0[0], u0[1]}), hb = pg8::silu_mul_pk((f32x2){g0[2], g0[3]}, (f32x2){u0[2], u0[3]});
;                 const f32x2 hc = pg8::silu_mul_pk((f32x2){g1[0], g1[1]}, (f32x2){u1[0], u1[1]}), hd = pg8::silu_mul_pk((f32x2){g1[2], g1[3]}, (f32x2){u1[2], u1[3]});
;                 u32x4 w; w.x = cvt_pk_bf16(ha.x, ha.y); w.y = cvt_pk_bf16(hb.x, hb.y); w.z = cvt_pk_bf16(hc.x, hc.y); w.w = cvt_pk_bf16(hd.x, hd.y);
;                 *(u32x4*)(H + (size_t)lr * FF + hcol) = w;
	v_rcp_f32_e32 v49, v49
	v_pk_add_f32 v[44:45], v[44:45], 1.0 op_sel_hi:[1,0]
	s_nop 0
	v_rcp_f32_e32 v44, v44
	v_rcp_f32_e32 v45, v45
	v_pk_mul_f32 v[36:37], v[36:37], v[48:49]
	v_pk_mul_f32 v[40:41], v[32:33], v[44:45]
	v_pk_mul_f32 v[32:33], v[42:43], s[88:89] op_sel_hi:[1,0]
	s_nop 0
	v_exp_f32_e32 v32, v32
	v_exp_f32_e32 v33, v33
	s_nop 0
	v_pk_add_f32 v[32:33], v[32:33], 1.0 op_sel_hi:[1,0]
	s_nop 0
	v_rcp_f32_e32 v32, v32
	v_rcp_f32_e32 v33, v33
	s_nop 0
	v_pk_mul_f32 v[42:43], v[34:35], v[32:33]
	v_cvt_pk_bf16_f32 v32, v36, v37
	v_mad_i64_i32 v[36:37], s[26:27], v50, s2, v[128:129]
	v_cvt_pk_bf16_f32 v33, v38, v39
	v_lshl_add_u64 v[36:37], v[36:37], 0, v[130:131]
	v_cvt_pk_bf16_f32 v34, v40, v41
	v_cvt_pk_bf16_f32 v35, v42, v43
	global_store_dwordx4 v[36:37], v[32:35], off
	s_nop 1
	v_pk_mul_f32 v[32:33], v[28:29], s[88:89] op_sel_hi:[1,0]
	v_pk_mul_f32 v[28:29], v[30:31], s[88:89] op_sel_hi:[1,0]
	v_exp_f32_e32 v32, v32
	v_exp_f32_e32 v28, v28
	v_exp_f32_e32 v29, v29
	v_exp_f32_e32 v33, v33
	v_add_u32_e32 v34, 0xa0, v165
	v_pk_add_f32 v[28:29], v[28:29], 1.0 op_sel_hi:[1,0]
	s_nop 0
	v_rcp_f32_e32 v28, v28
	v_rcp_f32_e32 v29, v29
	v_pk_add_f32 v[32:33], v[32:33], 1.0 op_sel_hi:[1,0]
	v_pk_mul_f32 v[22:23], v[22:23], v[28:29]
	v_pk_mul_f32 v[28:29], v[24:25], s[88:89] op_sel_hi:[1,0]
	v_rcp_f32_e32 v32, v32
	v_exp_f32_e32 v28, v28
	v_exp_f32_e32 v29, v29
	v_rcp_f32_e32 v33, v33
	v_pk_add_f32 v[28:29], v[28:29], 1.0 op_sel_hi:[1,0]
	s_nop 0
	v_rcp_f32_e32 v28, v28
	v_rcp_f32_e32 v29, v29
	v_pk_mul_f32 v[20:21], v[20:21], v[32:33]
	v_pk_mul_f32 v[24:25], v[16:17], v[28:29]
	v_pk_mul_f32 v[16:17], v[26:27], s[88:89] op_sel_hi:[1,0]
	s_nop 0
	v_exp_f32_e32 v16, v16
	v_exp_f32_e32 v17, v17
	s_nop 0
	v_pk_add_f32 v[16:17], v[16:17], 1.0 op_sel_hi:[1,0]
	s_nop 0
	v_rcp_f32_e32 v16, v16
	v_rcp_f32_e32 v17, v17
	s_nop 0
	v_pk_mul_f32 v[26:27], v[18:19], v[16:17]
	v_cvt_pk_bf16_f32 v16, v20, v21
	v_mad_i64_i32 v[20:21], s[26:27], v34, s2, v[128:129]
	v_cvt_pk_bf16_f32 v17, v22, v23
	v_lshl_add_u64 v[20:21], v[20:21], 0, v[130:131]
	v_cvt_pk_bf16_f32 v18, v24, v25
	v_cvt_pk_bf16_f32 v19, v26, v27
	global_store_dwordx4 v[20:21], v[16:19], off
	s_nop 1
	v_pk_mul_f32 v[16:17], v[12:13], s[88:89] op_sel_hi:[1,0]
	v_pk_mul_f32 v[12:13], v[14:15], s[88:89] op_sel_hi:[1,0]
	v_exp_f32_e32 v16, v16
	v_exp_f32_e32 v12, v12
	v_exp_f32_e32 v13, v13
	v_exp_f32_e32 v17, v17
	v_add_u32_e32 v18, 0xb0, v165
	v_pk_add_f32 v[12:13], v[12:13], 1.0 op_sel_hi:[1,0]
	s_nop 0
	v_rcp_f32_e32 v12, v12
	v_rcp_f32_e32 v13, v13
	v_pk_add_f32 v[16:17], v[16:17], 1.0 op_sel_hi:[1,0]
	v_pk_mul_f32 v[6:7], v[6:7], v[12:13]
	v_pk_mul_f32 v[12:13], v[8:9], s[88:89] op_sel_hi:[1,0]
	v_rcp_f32_e32 v16, v16
	v_exp_f32_e32 v12, v12
	v_exp_f32_e32 v13, v13
	v_rcp_f32_e32 v17, v17
	v_pk_add_f32 v[12:13], v[12:13], 1.0 op_sel_hi:[1,0]
	s_nop 0
	v_rcp_f32_e32 v12, v12
	v_rcp_f32_e32 v13, v13
	v_pk_mul_f32 v[4:5], v[4:5], v[16:17]
	v_pk_mul_f32 v[8:9], v[0:1], v[12:13]
	v_pk_mul_f32 v[0:1], v[10:11], s[88:89] op_sel_hi:[1,0]
	s_nop 0
	v_exp_f32_e32 v0, v0
	v_exp_f32_e32 v1, v1
	s_nop 0
	v_pk_add_f32 v[0:1], v[0:1], 1.0 op_sel_hi:[1,0]
	s_nop 0
	v_rcp_f32_e32 v0, v0
	v_rcp_f32_e32 v1, v1
	s_nop 0
	v_pk_mul_f32 v[10:11], v[2:3], v[0:1]
	v_cvt_pk_bf16_f32 v0, v4, v5
	v_mad_i64_i32 v[4:5], s[26:27], v18, s2, v[128:129]
	v_lshl_add_u64 v[4:5], v[4:5], 0, v[130:131]
	s_mov_b64 s[26:27], -1
	v_cvt_pk_bf16_f32 v1, v6, v7
	v_cvt_pk_bf16_f32 v2, v8, v9
	v_cvt_pk_bf16_f32 v3, v10, v11
	global_store_dwordx4 v[4:5], v[0:3], off
	s_cbranch_vccnz .LBB0_369
	s_and_b64 vcc, exec, s[34:35]
	s_cbranch_vccnz .LBB0_368
	s_branch .LBB0_368
